# diff-attn softmax: packed f32 math (v_pk_fma_f32 scale in place, v_pk_add_f32 sum tree), 32 fewer VALU per tile
# baseline (speedup 1.0000x reference)
; #define LAS __attribute__((address_space(3)))
; __device__ __forceinline__ int v_rd_base(int lane) { return ((lane & 3) << 3) | (((lane >> 2) & 3) << 6) | (((lane >> 4) & 1) << 5) | (((lane >> 5) & 1) << 8); }
; __device__ __forceinline__ int swap23(int k) { return (k & ~0xC) | ((k & 4) << 1) | ((k & 8) >> 1); }
; #define A3_BAR() do { asm volatile("s_waitcnt vmcnt(0) lgkmcnt(0)" ::: "memory"); __builtin_amdgcn_s_barrier(); asm volatile("" ::: "memory"); } while (0)
; #define lane lane_id()
; __device__ __forceinline__ void attn_block3(const BlockRef& cur, char* lds, const int wid) {
;     const int lane = lane_id(), r32 = lane & 31, hi = lane >> 5;
;     const int NT = (cur.P0 + QB - 1) / KVBLK + 1;
;     const int qlo = cur.P0 + wid * QBLK, qm = qlo + r32 - 4 * hi;
;     char* V_lds = lds + A3_V; char* K_lds = lds + A3_K;
;     float* ws = (float*)(lds + A3_WS) + wid * 64; float* li_l = ws, * al_l = ws + 32;
;     const float* tb = cur.tb;
;     unsigned kgo[2], vgo[2];
; #pragma unroll
;     for (int i = 0; i < 2; ++i) { const int pc = 2 * wid + i;
;         const int row = 4 * pc + (lane >> 4), c = (lane & 15) ^ (row & 7); kgo[i] = (unsigned)(row * 256 + c * 16);
;         const int sub = 2 * pc + (lane >> 5), kk = (sub >> 2) * 8 + ((lane & 31) >> 2), k = swap23(kk), cc = (sub & 3) * 32 + (lane & 3) * 8; vgo[i] = (unsigned)(k * 256 + cc * 2); }
;     bf16x8 qr[8];
; #pragma unroll
;     for (int d0 = 0; d0 < 8; ++d0) qr[d0] = load8(cur.Q + (size_t)(wid * QBLK + r32) * D + d0 * 16 + hi * 8);
;     LAS unsigned char* ldsl = (LAS unsigned char*)lds;
;     const char* Kg = (const char*)cur.K; const char* Vg = (const char*)cur.V; const char* Vg2 = (const char*)cur.V2;
;     ...
;     A3_DMA(0);
;     A3_BAR();
;     float m_reg = -1e30f, l_reg = 0; f32x16 o[4] = {}, o2[4] = {};
;     const int vbase = (int)(uintptr_t)V_lds + v_rd_base(lane);
; __global__ void __launch_bounds__(512, 2) mega_fwd(Args args) {
;     ...
;                 __syncthreads();
;                 if (tid == 0) *qw = atomicAdd(qctr + vq, 1u);
;                 __syncthreads();
;                 const unsigned w = (unsigned)__builtin_amdgcn_readfirstlane((int)*qw);
;                 if (w >= 64u) break;
;                 att::attn_block3(refq(vq, 63 - (int)w), (char*)lds, wave);
.LBB0_447:
	s_or_b64 exec, exec, s[4:5]
	s_cmp_lg_u32 s77, -1
	s_cselect_b32 s4, s77, 0
	s_cselect_b32 s5, s11, 0
	v_mov_b32_e32 v2, s4
	v_mov_b32_e32 v3, s5
	s_waitcnt lgkmcnt(0)
	s_barrier
	flat_load_dword v0, v[2:3] sc0 sc1
	s_waitcnt vmcnt(0)
	s_mov_b64 s[4:5], -1
	s_waitcnt lgkmcnt(0)
	v_readfirstlane_b32 s6, v0
	s_cmp_gt_u32 s6, 63
	s_cbranch_scc1 .LBB0_442
	s_sub_i32 s44, 63, s6
	s_lshl_b32 s4, s44, 16
	v_mbcnt_lo_u32_b32 v239, -1, 0
	v_mbcnt_hi_u32_b32 v239, -1, v239
	s_or_b32 s4, s4, s78
	v_bfe_u32 v9, v239, 4, 2
	v_and_b32_e32 v0, 15, v239
	v_and_b32_e32 v238, 31, v239
	v_bitop3_b32 v0, v9, v0, 4 bitop3:0x36
	s_add_u32 s4, s34, s4
	v_bitop3_b32 v5, v9, v239, 15 bitop3:0x78
	v_lshlrev_b32_e32 v14, 4, v0
	v_or_b32_e32 v0, s39, v238
	s_addc_u32 s5, s35, 0
	v_and_b32_e32 v8, 63, v239
	v_bfe_u32 v2, v239, 2, 3
	v_or_b32_e32 v4, s15, v9
	v_lshlrev_b32_e32 v13, 4, v5
	v_bfe_u32 v16, v239, 5, 1
	v_lshlrev_b32_e32 v0, 8, v0
	v_bitop3_b32 v10, v2, 51, s15 bitop3:0xc8
	v_lshrrev_b32_e32 v2, 1, v239
	v_and_b32_e32 v3, 32, v239
	v_lshlrev_b32_e32 v12, 3, v8
	v_lshl_or_b32 v6, v4, 8, v13
	v_lshl_add_u64 v[4:5], s[4:5], 0, v[0:1]
	v_lshlrev_b32_e32 v0, 4, v16
	v_and_b32_e32 v11, 8, v2
	v_and_or_b32 v3, v12, 24, v3
	v_lshl_add_u64 v[4:5], v[4:5], 0, v[0:1]
	v_or3_b32 v2, v11, v10, s81
	v_lshlrev_b32_e32 v3, 1, v3
	global_load_dwordx4 v[192:195], v[4:5], off
	global_load_dwordx4 v[196:199], v[4:5], off offset:32
	global_load_dwordx4 v[200:203], v[4:5], off offset:64
	global_load_dwordx4 v[204:207], v[4:5], off offset:96
	global_load_dwordx4 v[208:211], v[4:5], off offset:128
	global_load_dwordx4 v[212:215], v[4:5], off offset:160
	global_load_dwordx4 v[216:219], v[4:5], off offset:192
	global_load_dwordx4 v[220:223], v[4:5], off offset:224
	s_mov_b32 m0, s83
	v_lshl_or_b32 v2, v2, 8, v3
	v_or_b32_e32 v3, 4, v9
	v_or_b32_e32 v3, s15, v3
	global_load_lds_dwordx4 v6, s[56:57]
	s_mov_b32 m0, s82
	v_lshl_or_b32 v15, v3, 8, v14
	v_mov_b32_e32 v3, v1
	global_load_lds_dwordx4 v2, s[58:59]
	s_add_i32 m0, s82, 0x4000
	v_lshl_add_u64 v[4:5], s[58:59], 0, v[2:3]
	global_load_lds_dwordx4 v2, s[62:63]
	s_add_i32 m0, s82, 0x10400
	v_lshl_add_u64 v[6:7], s[62:63], 0, v[2:3]
	global_load_lds_dwordx4 v15, s[56:57]
	v_lshl_add_u64 v[2:3], v[4:5], 0, s[46:47]
	s_add_i32 m0, s82, 0x400
	s_lshl_b32 s7, s44, 8
	global_load_lds_dwordx4 v[2:3], off
	v_lshl_add_u64 v[2:3], v[6:7], 0, s[46:47]
	s_add_i32 m0, s82, 0x4400
	s_lshl_b32 s4, s44, 2
	global_load_lds_dwordx4 v[2:3], off
	s_or_b32 s79, s7, s39
	s_or_b32 s87, s4, 3
	v_lshlrev_b32_e32 v3, 4, v239
	s_movk_i32 s4, 0x70
	v_and_b32_e32 v2, 0x118, v12
	v_and_b32_e32 v4, 0xc0, v3
	v_and_b32_e32 v5, 0x70, v3
	v_bitop3_b32 v242, v0, v3, s4 bitop3:0x78
	v_lshlrev_b32_e32 v3, 1, v239
	s_cmp_lg_u32 0, -1
	s_movk_i32 s4, 0x60
	v_and_or_b32 v2, v3, 32, v2
	s_cselect_b32 s7, 0, 0
	v_bitop3_b32 v243, v0, v5, 32 bitop3:0x36
	v_bitop3_b32 v244, v0, v5, 64 bitop3:0x36
	v_bitop3_b32 v245, v0, v5, s4 bitop3:0x36
	v_lshlrev_b32_e32 v5, 2, v238
	v_add3_u32 v246, v4, s7, v2
	s_lshl_b32 s7, s6, 2
	v_add_u32_e32 v2, s81, v10
	v_and_b32_e32 v4, 3, v239
	v_add_u32_e32 v237, s1, v0
	s_sub_i32 s88, 0x100, s7
	v_add_lshl_u32 v2, v2, v11, 8
	v_and_b32_e32 v3, 64, v3
	v_lshlrev_b32_e32 v4, 4, v4
	v_sub_u32_e32 v0, v5, v0
	s_lshl_b32 s7, s6, 10
	v_or3_b32 v2, v2, v3, v4
	v_mov_b32_e32 v3, v1
	v_lshlrev_b32_e32 v4, 8, v9
	v_subrev_u32_e32 v0, s7, v0
	v_lshlrev_b32_e32 v236, 2, v16
	v_mov_b32_e32 v224, v2
	v_add_u32_e32 v225, 0x80, v2
	v_add3_u32 v2, s86, v4, v13
	v_add_u32_e32 v247, s75, v0
	v_add_u32_e32 v0, s76, v238
	s_waitcnt vmcnt(0) lgkmcnt(0)
	s_barrier
	v_mov_b32_e32 v228, v2
	v_add3_u32 v2, s74, v4, v14
	v_sub_u32_e32 v0, v0, v236
	s_lshl_b32 s6, s6, 8
	v_mov_b32_e32 v14, v1
	v_mov_b32_e32 v15, v1
	v_cmp_gt_u32_e64 s[4:5], 32, v8
	v_add_u32_e32 v241, s1, v5
	v_mov_b32_e32 v230, v2
	v_subrev_u32_e32 v248, s6, v0
	v_mov_b32_e32 v0, v1
	v_mov_b32_e32 v2, v1
	v_mov_b32_e32 v4, v1
	v_mov_b32_e32 v5, v1
	v_mov_b32_e32 v6, v1
	v_mov_b32_e32 v7, v1
	v_mov_b32_e32 v8, v1
	v_mov_b32_e32 v9, v1
	v_mov_b32_e32 v10, v1
	v_mov_b32_e32 v11, v1
	v_mov_b32_e32 v12, v1
	v_mov_b32_e32 v13, v1
	v_mov_b64_e32 v[30:31], v[14:15]
	v_mov_b64_e32 v[62:63], v[14:15]
	v_mov_b64_e32 v[94:95], v[14:15]
	v_mov_b64_e32 v[126:127], v[14:15]
	v_mov_b64_e32 v[46:47], v[14:15]
	v_mov_b64_e32 v[78:79], v[14:15]
	v_mov_b64_e32 v[110:111], v[14:15]
	v_mov_b64_e32 v[142:143], v[14:15]
	v_lshlrev_b32_e32 v240, 8, v238
	s_mov_b32 s93, 0
	v_mov_b32_e32 v250, 0
	v_mov_b32_e32 v249, 0xf149f2ca
	v_mov_b32_e32 v252, 0x3e0293ee
	v_mov_b32_e32 v253, 0x3e0293ee
	s_movk_i32 s90, 0xb0
	s_add_u32 s68, s18, s66
	s_addc_u32 s69, s19, s67
	s_add_u32 s98, s18, s64
	s_addc_u32 s99, s19, s65
	s_add_u32 s98, s98, s48
	s_addc_u32 s99, s99, s49
	s_add_u32 s100, s18, s60
	s_addc_u32 s101, s19, s61
	s_add_u32 s100, s100, s48
	s_addc_u32 s101, s101, s49
	v_mov_b64_e32 v[28:29], v[12:13]
	v_mov_b64_e32 v[26:27], v[10:11]
	v_mov_b64_e32 v[24:25], v[8:9]
	v_mov_b64_e32 v[22:23], v[6:7]
	v_mov_b64_e32 v[20:21], v[4:5]
	v_mov_b64_e32 v[18:19], v[2:3]
	v_mov_b64_e32 v[16:17], v[0:1]
	v_mov_b64_e32 v[60:61], v[12:13]
	v_mov_b64_e32 v[58:59], v[10:11]
	v_mov_b64_e32 v[56:57], v[8:9]
	v_mov_b64_e32 v[54:55], v[6:7]
	v_mov_b64_e32 v[52:53], v[4:5]
	v_mov_b64_e32 v[50:51], v[2:3]
	v_mov_b64_e32 v[48:49], v[0:1]
	v_mov_b64_e32 v[92:93], v[12:13]
	v_mov_b64_e32 v[90:91], v[10:11]
	v_mov_b64_e32 v[88:89], v[8:9]
	v_mov_b64_e32 v[86:87], v[6:7]
	v_mov_b64_e32 v[84:85], v[4:5]
	v_mov_b64_e32 v[82:83], v[2:3]
	v_mov_b64_e32 v[80:81], v[0:1]
	v_mov_b64_e32 v[124:125], v[12:13]
	v_mov_b64_e32 v[122:123], v[10:11]
	v_mov_b64_e32 v[120:121], v[8:9]
	v_mov_b64_e32 v[118:119], v[6:7]
	v_mov_b64_e32 v[116:117], v[4:5]
	v_mov_b64_e32 v[114:115], v[2:3]
	v_mov_b64_e32 v[112:113], v[0:1]
	v_mov_b64_e32 v[44:45], v[12:13]
	v_mov_b64_e32 v[42:43], v[10:11]
	v_mov_b64_e32 v[40:41], v[8:9]
	v_mov_b64_e32 v[38:39], v[6:7]
	v_mov_b64_e32 v[36:37], v[4:5]
	v_mov_b64_e32 v[34:35], v[2:3]
	v_mov_b64_e32 v[32:33], v[0:1]
	v_mov_b64_e32 v[76:77], v[12:13]
	v_mov_b64_e32 v[74:75], v[10:11]
	v_mov_b64_e32 v[72:73], v[8:9]
	v_mov_b64_e32 v[70:71], v[6:7]
	v_mov_b64_e32 v[68:69], v[4:5]
	v_mov_b64_e32 v[66:67], v[2:3]
	v_mov_b64_e32 v[64:65], v[0:1]
	v_mov_b64_e32 v[108:109], v[12:13]
	v_mov_b64_e32 v[106:107], v[10:11]
	v_mov_b64_e32 v[104:105], v[8:9]
	v_mov_b64_e32 v[102:103], v[6:7]
	v_mov_b64_e32 v[100:101], v[4:5]
	v_mov_b64_e32 v[98:99], v[2:3]
	v_mov_b64_e32 v[96:97], v[0:1]
	v_mov_b64_e32 v[140:141], v[12:13]
	v_mov_b64_e32 v[138:139], v[10:11]
	v_mov_b64_e32 v[136:137], v[8:9]
	v_mov_b64_e32 v[134:135], v[6:7]
	v_mov_b64_e32 v[132:133], v[4:5]
	v_mov_b64_e32 v[130:131], v[2:3]
	v_mov_b64_e32 v[128:129], v[0:1]
	s_waitcnt vmcnt(0)

; __device__ __forceinline__ void partialSM(f32x16& p0, f32x16& p1, float& m_reg, float& mn, float& alpha) {
;     ...
;     constexpr float C2 = 1.4426950408889634f * SM_SCALE;
;     if (__builtin_expect(__all((pmax - m_reg) * SM_SCALE <= THR), 1)) { mn = m_reg; alpha = 1.f; }
;     else { mn = fmaxf(m_reg, pmax); alpha = __builtin_amdgcn_exp2f((m_reg - mn) * C2); m_reg = mn; }
;     const float mnL = -mn * C2;
; #pragma unroll
;     for (int r = 0; r < 16; ++r) p0[r] = fmaf(p0[r], C2, mnL);
; #pragma unroll
;     for (int r = 0; r < 16; ++r) p1[r] = fmaf(p1[r], C2, mnL);
; #pragma unroll
;     for (int r = 0; r < 16; ++r) p0[r] = __builtin_amdgcn_exp2f(p0[r]);
; }
; __device__ __forceinline__ void finishSM(f32x16& p0, f32x16& p1, float alpha, float& l_reg, bf16x8& pa0, bf16x8& pa1, bf16x8& pa2, bf16x8& pa3) {
; #pragma unroll
;     for (int r = 0; r < 16; ++r) p1[r] = __builtin_amdgcn_exp2f(p1[r]);
;     float ps = 0;
; #pragma unroll
;     for (int r = 0; r < 16; ++r) ps += p0[r];
; #pragma unroll
;     for (int r = 0; r < 16; ++r) ps += p1[r];
;     { auto rr = __builtin_amdgcn_permlane32_swap(__float_as_uint(ps), __float_as_uint(ps), false, false);
;       ps = __uint_as_float(rr[0]) + __uint_as_float(rr[1]); }
;     l_reg = l_reg * alpha + ps;
;     PK4(p0, 0, pa0); PK4(p0, 8, pa1); PK4(p1, 0, pa2); PK4(p1, 8, pa3);
.Ldiff_join:
	v_mul_f32_e32 v2, 0xbe0293ee, v249
	v_pk_fma_f32 v[160:161], v[160:161], v[252:253], v[2:3] op_sel_hi:[1,0,0]
	v_pk_fma_f32 v[162:163], v[162:163], v[252:253], v[2:3] op_sel_hi:[1,0,0]
	v_pk_fma_f32 v[164:165], v[164:165], v[252:253], v[2:3] op_sel_hi:[1,0,0]
	v_pk_fma_f32 v[166:167], v[166:167], v[252:253], v[2:3] op_sel_hi:[1,0,0]
	v_exp_f32_e32 v160, v160
	v_pk_fma_f32 v[168:169], v[168:169], v[252:253], v[2:3] op_sel_hi:[1,0,0]
	v_exp_f32_e32 v161, v161
	v_exp_f32_e32 v162, v162
	v_pk_fma_f32 v[170:171], v[170:171], v[252:253], v[2:3] op_sel_hi:[1,0,0]
	v_exp_f32_e32 v163, v163
	v_exp_f32_e32 v164, v164
	v_pk_fma_f32 v[172:173], v[172:173], v[252:253], v[2:3] op_sel_hi:[1,0,0]
	v_exp_f32_e32 v165, v165
	v_exp_f32_e32 v166, v166
	v_pk_fma_f32 v[174:175], v[174:175], v[252:253], v[2:3] op_sel_hi:[1,0,0]
	v_exp_f32_e32 v167, v167
	v_pk_add_f32 v[4:5], v[160:161], v[162:163]
	v_exp_f32_e32 v168, v168
	v_pk_fma_f32 v[144:145], v[144:145], v[252:253], v[2:3] op_sel_hi:[1,0,0]
	v_exp_f32_e32 v169, v169
	v_exp_f32_e32 v170, v170
	v_pk_fma_f32 v[146:147], v[146:147], v[252:253], v[2:3] op_sel_hi:[1,0,0]
	v_exp_f32_e32 v171, v171
	v_pk_add_f32 v[6:7], v[164:165], v[166:167]
	v_exp_f32_e32 v172, v172
	v_pk_fma_f32 v[148:149], v[148:149], v[252:253], v[2:3] op_sel_hi:[1,0,0]
	v_exp_f32_e32 v173, v173
	v_pk_add_f32 v[4:5], v[4:5], v[168:169]
	v_exp_f32_e32 v174, v174
	v_pk_fma_f32 v[150:151], v[150:151], v[252:253], v[2:3] op_sel_hi:[1,0,0]
	v_exp_f32_e32 v175, v175
	v_pk_add_f32 v[6:7], v[6:7], v[170:171]
	v_exp_f32_e32 v144, v144
	v_pk_fma_f32 v[152:153], v[152:153], v[252:253], v[2:3] op_sel_hi:[1,0,0]
	v_exp_f32_e32 v145, v145
	v_pk_add_f32 v[4:5], v[4:5], v[172:173]
	v_exp_f32_e32 v146, v146
	v_pk_fma_f32 v[154:155], v[154:155], v[252:253], v[2:3] op_sel_hi:[1,0,0]
	v_exp_f32_e32 v147, v147
	v_pk_add_f32 v[6:7], v[6:7], v[174:175]
	v_exp_f32_e32 v148, v148
	v_pk_fma_f32 v[156:157], v[156:157], v[252:253], v[2:3] op_sel_hi:[1,0,0]
	v_exp_f32_e32 v149, v149
	v_pk_add_f32 v[4:5], v[4:5], v[144:145]
	v_exp_f32_e32 v150, v150
	v_pk_fma_f32 v[158:159], v[158:159], v[252:253], v[2:3] op_sel_hi:[1,0,0]
	v_exp_f32_e32 v151, v151
	v_pk_add_f32 v[6:7], v[6:7], v[146:147]
	v_exp_f32_e32 v152, v152
	v_exp_f32_e32 v153, v153
	v_pk_add_f32 v[4:5], v[4:5], v[148:149]
	v_exp_f32_e32 v154, v154
	v_exp_f32_e32 v155, v155
	v_pk_add_f32 v[6:7], v[6:7], v[150:151]
	v_exp_f32_e32 v156, v156
	v_exp_f32_e32 v157, v157
	v_pk_add_f32 v[4:5], v[4:5], v[152:153]
	v_exp_f32_e32 v158, v158
	v_exp_f32_e32 v159, v159
	v_pk_add_f32 v[6:7], v[6:7], v[154:155]
	v_pk_add_f32 v[4:5], v[4:5], v[156:157]
	v_pk_add_f32 v[6:7], v[6:7], v[158:159]
	v_pk_add_f32 v[4:5], v[4:5], v[6:7]
	v_add_f32_e32 v2, v4, v5
	v_mov_b32_e32 v6, v2
	s_nop 1
	v_permlane32_swap_b32_e32 v2, v6
	v_add_f32_e32 v14, v2, v6
	v_fma_f32 v250, v250, v0, v14
	v_cvt_pk_bf16_f32 v6, v160, v161
	v_cvt_pk_bf16_f32 v7, v162, v163
	v_cvt_pk_bf16_f32 v8, v164, v165
	v_cvt_pk_bf16_f32 v9, v166, v167
	v_cvt_pk_bf16_f32 v10, v168, v169
	v_cvt_pk_bf16_f32 v11, v170, v171
	v_cvt_pk_bf16_f32 v12, v172, v173
	v_cvt_pk_bf16_f32 v13, v174, v175
	v_cvt_pk_bf16_f32 v144, v144, v145
	v_cvt_pk_bf16_f32 v145, v146, v147
	v_cvt_pk_bf16_f32 v146, v148, v149
	v_cvt_pk_bf16_f32 v147, v150, v151
	v_cvt_pk_bf16_f32 v2, v152, v153
	v_cvt_pk_bf16_f32 v3, v154, v155
	v_cvt_pk_bf16_f32 v4, v156, v157
	v_cvt_pk_bf16_f32 v5, v158, v159
	s_nop 0
	v_permlane32_swap_b32_e32 v6, v8
	v_permlane32_swap_b32_e32 v7, v9
	v_permlane32_swap_b32_e32 v10, v12
	v_permlane32_swap_b32_e32 v11, v13
	v_permlane32_swap_b32_e32 v144, v146
	v_permlane32_swap_b32_e32 v145, v147
	v_permlane32_swap_b32_e32 v2, v4
	v_permlane32_swap_b32_e32 v3, v5
	v_lshl_add_u32 v0, s95, 15, v246
	ds_read_b64_tr_b16 v[148:149], v0 offset:0
	ds_read_b64_tr_b16 v[150:151], v0 offset:0x800
	ds_read_b64_tr_b16 v[152:153], v0 offset:0x4000
	ds_read_b64_tr_b16 v[154:155], v0 offset:0x4800
	ds_read_b64_tr_b16 v[156:157], v0 offset:0x1000
	ds_read_b64_tr_b16 v[158:159], v0 offset:0x1800
	ds_read_b64_tr_b16 v[160:161], v0 offset:0x5000
	ds_read_b64_tr_b16 v[162:163], v0 offset:0x5800
	ds_read_b64_tr_b16 v[164:165], v0 offset:0x2000
	ds_read_b64_tr_b16 v[166:167], v0 offset:0x2800
	ds_read_b64_tr_b16 v[168:169], v0 offset:0x6000
	ds_read_b64_tr_b16 v[170:171], v0 offset:0x6800
	ds_read_b64_tr_b16 v[172:173], v0 offset:0x3000
	ds_read_b64_tr_b16 v[174:175], v0 offset:0x3800
	ds_read_b64_tr_b16 v[176:177], v0 offset:0x7000
	ds_read_b64_tr_b16 v[178:179], v0 offset:0x7800
	s_waitcnt lgkmcnt(0)
; #define A3_BAR() do { asm volatile("s_waitcnt vmcnt(0) lgkmcnt(0)" ::: "memory"); __builtin_amdgcn_s_barrier(); asm volatile("" ::: "memory"); } while (0)
; __device__ __forceinline__ void pv_tile2(f32x16* o, f32x16* o2, int vb0, bf16x8 pa0, bf16x8 pa1, bf16x8 pa2, bf16x8 pa3) {
;     ...
;     PV2_D0(0); PV2_D0(1); PV2_D0(2); PV2_D0(3);
;     ...
; }
; __device__ __forceinline__ void attn_block3(const BlockRef& cur, char* lds, const int wid) {
;     ...
;         pv_tile2(o, o2, vbase + (t & 1) * 2 * SHM_V, pa0, pa1, pa2, pa3);
;         A3_BAR();
	s_nop 0
	v_mfma_f32_32x32x16_bf16 v[112:127], v[6:9], v[148:151], v[112:127]
	ds_read_b64_tr_b16 v[148:149], v0 offset:0x200
	ds_read_b64_tr_b16 v[150:151], v0 offset:0xa00
	v_mfma_f32_32x32x16_bf16 v[128:143], v[6:9], v[152:155], v[128:143]
	ds_read_b64_tr_b16 v[152:153], v0 offset:0x4200
	ds_read_b64_tr_b16 v[154:155], v0 offset:0x4a00
	v_mfma_f32_32x32x16_bf16 v[112:127], v[10:13], v[156:159], v[112:127]
	ds_read_b64_tr_b16 v[156:157], v0 offset:0x1200
	ds_read_b64_tr_b16 v[158:159], v0 offset:0x1a00
	v_mfma_f32_32x32x16_bf16 v[128:143], v[10:13], v[160:163], v[128:143]
	ds_read_b64_tr_b16 v[160:161], v0 offset:0x5200
	ds_read_b64_tr_b16 v[162:163], v0 offset:0x5a00
	v_mfma_f32_32x32x16_bf16 v[112:127], v[144:147], v[164:167], v[112:127]
	ds_read_b64_tr_b16 v[164:165], v0 offset:0x2200
	ds_read_b64_tr_b16 v[166:167], v0 offset:0x2a00
	v_mfma_f32_32x32x16_bf16 v[128:143], v[144:147], v[168:171], v[128:143]
	ds_read_b64_tr_b16 v[168:169], v0 offset:0x6200
	ds_read_b64_tr_b16 v[170:171], v0 offset:0x6a00
	v_mfma_f32_32x32x16_bf16 v[112:127], v[2:5], v[172:175], v[112:127]
	ds_read_b64_tr_b16 v[172:173], v0 offset:0x3200
	ds_read_b64_tr_b16 v[174:175], v0 offset:0x3a00
	v_mfma_f32_32x32x16_bf16 v[128:143], v[2:5], v[176:179], v[128:143]
	ds_read_b64_tr_b16 v[176:177], v0 offset:0x7200
	ds_read_b64_tr_b16 v[178:179], v0 offset:0x7a00
	s_waitcnt lgkmcnt(0)
	v_mfma_f32_32x32x16_bf16 v[80:95], v[6:9], v[148:151], v[80:95]
	ds_read_b64_tr_b16 v[148:149], v0 offset:0x400
	ds_read_b64_tr_b16 v[150:151], v0 offset:0xc00
	v_mfma_f32_32x32x16_bf16 v[96:111], v[6:9], v[152:155], v[96:111]
	ds_read_b64_tr_b16 v[152:153], v0 offset:0x4400
	ds_read_b64_tr_b16 v[154:155], v0 offset:0x4c00
	v_mfma_f32_32x32x16_bf16 v[80:95], v[10:13], v[156:159], v[80:95]
	ds_read_b64_tr_b16 v[156:157], v0 offset:0x1400
	ds_read_b64_tr_b16 v[158:159], v0 offset:0x1c00
	v_mfma_f32_32x32x16_bf16 v[96:111], v[10:13], v[160:163], v[96:111]
	ds_read_b64_tr_b16 v[160:161], v0 offset:0x5400
	ds_read_b64_tr_b16 v[162:163], v0 offset:0x5c00
	v_mfma_f32_32x32x16_bf16 v[80:95], v[144:147], v[164:167], v[80:95]
	ds_read_b64_tr_b16 v[164:165], v0 offset:0x2400
	ds_read_b64_tr_b16 v[166:167], v0 offset:0x2c00
	v_mfma_f32_32x32x16_bf16 v[96:111], v[144:147], v[168:171], v[96:111]
	ds_read_b64_tr_b16 v[168:169], v0 offset:0x6400
	ds_read_b64_tr_b16 v[170:171], v0 offset:0x6c00
	v_mfma_f32_32x32x16_bf16 v[80:95], v[2:5], v[172:175], v[80:95]
	ds_read_b64_tr_b16 v[172:173], v0 offset:0x3400
	ds_read_b64_tr_b16 v[174:175], v0 offset:0x3c00
	v_mfma_f32_32x32x16_bf16 v[96:111], v[2:5], v[176:179], v[96:111]
	ds_read_b64_tr_b16 v[176:177], v0 offset:0x7400
	ds_read_b64_tr_b16 v[178:179], v0 offset:0x7c00
	s_waitcnt lgkmcnt(0)
	v_mfma_f32_32x32x16_bf16 v[48:63], v[6:9], v[148:151], v[48:63]
	ds_read_b64_tr_b16 v[148:149], v0 offset:0x600
	ds_read_b64_tr_b16 v[150:151], v0 offset:0xe00
	v_mfma_f32_32x32x16_bf16 v[64:79], v[6:9], v[152:155], v[64:79]
	ds_read_b64_tr_b16 v[152:153], v0 offset:0x4600
	ds_read_b64_tr_b16 v[154:155], v0 offset:0x4e00
	v_mfma_f32_32x32x16_bf16 v[48:63], v[10:13], v[156:159], v[48:63]
	ds_read_b64_tr_b16 v[156:157], v0 offset:0x1600
	ds_read_b64_tr_b16 v[158:159], v0 offset:0x1e00
	v_mfma_f32_32x32x16_bf16 v[64:79], v[10:13], v[160:163], v[64:79]
	ds_read_b64_tr_b16 v[160:161], v0 offset:0x5600
	ds_read_b64_tr_b16 v[162:163], v0 offset:0x5e00
	v_mfma_f32_32x32x16_bf16 v[48:63], v[144:147], v[164:167], v[48:63]
	ds_read_b64_tr_b16 v[164:165], v0 offset:0x2600
	ds_read_b64_tr_b16 v[166:167], v0 offset:0x2e00
	v_mfma_f32_32x32x16_bf16 v[64:79], v[144:147], v[168:171], v[64:79]
	ds_read_b64_tr_b16 v[168:169], v0 offset:0x6600
	ds_read_b64_tr_b16 v[170:171], v0 offset:0x6e00
	v_mfma_f32_32x32x16_bf16 v[48:63], v[2:5], v[172:175], v[48:63]
	ds_read_b64_tr_b16 v[172:173], v0 offset:0x3600
	ds_read_b64_tr_b16 v[174:175], v0 offset:0x3e00
	v_mfma_f32_32x32x16_bf16 v[64:79], v[2:5], v[176:179], v[64:79]
	ds_read_b64_tr_b16 v[176:177], v0 offset:0x7600
	ds_read_b64_tr_b16 v[178:179], v0 offset:0x7e00
	s_waitcnt lgkmcnt(0)
	v_mfma_f32_32x32x16_bf16 v[16:31], v[6:9], v[148:151], v[16:31]
	s_waitcnt vmcnt(0) lgkmcnt(0)
	s_barrier
	s_add_u32 s68, s68, 0x4000
	s_addc_u32 s69, s69, 0
	s_add_u32 s98, s98, 0x4000
	s_addc_u32 s99, s99, 0
	s_add_u32 s100, s100, 0x4000
	s_addc_u32 s101, s101, 0
	s_add_i32 s90, s90, 64
	v_add_u32_e32 v247, 0xffffff00, v247
	v_mfma_f32_32x32x16_bf16 v[32:47], v[6:9], v[152:155], v[32:47]
	v_subrev_u32_e32 v248, 64, v248
	s_cmp_eq_u32 s88, s93
	v_mfma_f32_32x32x16_bf16 v[16:31], v[10:13], v[156:159], v[16:31]
	v_mfma_f32_32x32x16_bf16 v[32:47], v[10:13], v[160:163], v[32:47]
	v_mfma_f32_32x32x16_bf16 v[16:31], v[144:147], v[164:167], v[16:31]
	v_mfma_f32_32x32x16_bf16 v[32:47], v[144:147], v[168:171], v[32:47]
	v_mfma_f32_32x32x16_bf16 v[16:31], v[2:5], v[172:175], v[16:31]
	v_mfma_f32_32x32x16_bf16 v[32:47], v[2:5], v[176:179], v[32:47]
	s_cbranch_scc1 .LBB0_491
	s_branch .LBB0_449
